# DSA: level-1 radix count by DPP wave sum; P.V transposed reads issued pairwise with counted lgkmcnt
# speedup vs baseline: 1.0498x; 1.0041x over previous
;     ...
;               const unsigned cl = (acc - (unsigned)(8 * nblk) * (c - 1u) + basek) >> 16;
;               int cnt = 0;
; #pragma unroll
;               for (int b_ = 0; b_ < 7; ++b_) cnt += __builtin_popcountll(__ballot((cl >> b_) & 1u)) << b_;
;               if (cnt >= 256) { T15 = c; cntT = cnt; }
;               if (cnt == 256) { exact = true; break; }
.LBB0_454:
	v_mul_lo_u32 v105, v105, s65
	v_sub_u32_e32 v105, v70, v105
	v_add_u32_e32 v105, v106, v105
	v_bfe_u32 v106, v105, 16, 7
	s_nop 1
	v_add_u32_dpp v106, v106, v106 row_shr:1 row_mask:0xf bank_mask:0xf bound_ctrl:0
	s_nop 1
	v_add_u32_dpp v106, v106, v106 row_shr:2 row_mask:0xf bank_mask:0xf bound_ctrl:0
	s_nop 1
	v_add_u32_dpp v106, v106, v106 row_shr:4 row_mask:0xf bank_mask:0xf bound_ctrl:0
	s_nop 1
	v_add_u32_dpp v106, v106, v106 row_shr:8 row_mask:0xf bank_mask:0xf bound_ctrl:0
	s_nop 1
	v_add_u32_dpp v106, v106, v106 row_bcast:15 row_mask:0xa bank_mask:0xf
	s_nop 1
	v_add_u32_dpp v106, v106, v106 row_bcast:31 row_mask:0xc bank_mask:0xf
	s_nop 0
	v_readlane_b32 s66, v106, 63
	s_cmpk_gt_u32 s66, 0xff
	s_cselect_b32 s37, s66, s37
	s_cselect_b64 vcc, -1, 0
	s_cmpk_lg_i32 s66, 0x100
	s_cselect_b64 s[56:57], -1, 0
	s_cmpk_eq_i32 s66, 0x100
	v_cndmask_b32_e32 v102, v102, v104, vcc
	s_cselect_b64 s[66:67], -1, 0
	v_subrev_co_u32_e32 v103, vcc, 1, v103
	s_or_b64 s[66:67], s[66:67], vcc
	s_andn2_b64 vcc, exec, s[66:67]
	s_cbranch_vccz .LBB0_470

; #define LAS __attribute__((address_space(3)))
; __device__ __forceinline__ u16 f2bf(float f) { return (u16)(cvtpk(f, 0.f) & 0xffffu); }
;     ...
;               ss += __shfl_xor(ss, 16); ss += __shfl_xor(ss, 32);
;               const float rstd = rsqrtf(ss * (1.f / 128.f) + EPS);
;               const float av = quad == 0 ? a[0] : (quad == 1 ? a[1] : (quad == 2 ? a[2] : a[3]));
;               rsv[jj] = rstd; lgv[jj] = (slot < kcount) ? av * rstd * 0.08838834764831845f : -__builtin_inff();
;           }
;           if (b + 1 < nb) gl(b + 1);
;           float mx = fmaxf(fmaxf(lgv[0], lgv[1]), fmaxf(lgv[2], lgv[3]));
; #pragma unroll
;           for (int o = 1; o < 16; o <<= 1) mx = fmaxf(mx, __shfl_xor(mx, o));
;           const float mnew = fmaxf(mrun, mx), alpha = __expf(mrun - mnew); mrun = mnew;
;           float ps = 0.f;
; #pragma unroll
;           for (int jj = 0; jj < 4; ++jj) { const float pe = __expf(lgv[jj] - mnew); ps += pe; pbT[quad * 64 + jj * 16 + c16] = f2bf(pe * rsv[jj]); }
;           lsum = lsum * alpha + ps;
;           if (c16 == 0) alf[quad] = alpha;
;           const f32x4 al4 = *(const LAS f32x4*)alf;
.LBB0_946:
	s_waitcnt lgkmcnt(1)
	v_add_f32_e32 v119, v119, v175
	v_fmamk_f32 v119, v119, 0x3c000000, v199
	v_cmp_gt_f32_e32 vcc, s85, v119
	v_mul_f32_e32 v121, 0x4b800000, v119
	v_add_u32_e32 v0, 48, v157
	v_cndmask_b32_e32 v119, v119, v121, vcc
	v_rsq_f32_e32 v119, v119
	v_add_f32_e32 v117, v117, v174
	v_fmamk_f32 v117, v117, 0x3c000000, v199
	v_add_f32_e32 v115, v115, v173
	v_mul_f32_e32 v121, 0x45800000, v119
	v_cndmask_b32_e32 v122, v119, v121, vcc
	v_cmp_gt_i32_e32 vcc, s22, v0
	v_mul_f32_e32 v0, v122, v120
	v_mul_f32_e32 v0, 0x3db504f3, v0
	v_cndmask_b32_e32 v121, v208, v0, vcc
	v_cmp_gt_f32_e32 vcc, s85, v117
	v_mul_f32_e32 v119, 0x4b800000, v117
	v_add_u32_e32 v0, 32, v157
	v_cndmask_b32_e32 v117, v117, v119, vcc
	v_rsq_f32_e32 v117, v117
	v_fmamk_f32 v115, v115, 0x3c000000, v199
	v_mul_f32_e32 v119, 0x45800000, v117
	v_cndmask_b32_e32 v123, v117, v119, vcc
	v_cmp_gt_i32_e32 vcc, s22, v0
	v_mul_f32_e32 v0, v123, v118
	v_mul_f32_e32 v0, 0x3db504f3, v0
	v_cndmask_b32_e32 v120, v208, v0, vcc
	v_cmp_gt_f32_e32 vcc, s85, v115
	v_mul_f32_e32 v117, 0x4b800000, v115
	v_add_u32_e32 v0, 16, v157
	v_cndmask_b32_e32 v115, v115, v117, vcc
	v_rsq_f32_e32 v115, v115
	s_nop 0
	v_mul_f32_e32 v117, 0x45800000, v115
	v_cndmask_b32_e32 v125, v115, v117, vcc
	v_cmp_gt_i32_e32 vcc, s22, v0
	v_mul_f32_e32 v0, v125, v116
	v_mul_f32_e32 v0, 0x3db504f3, v0
	v_cndmask_b32_e32 v119, v208, v0, vcc
	v_add_f32_e32 v0, v161, v172
	v_fmamk_f32 v0, v0, 0x3c000000, v199
	v_cmp_gt_f32_e32 vcc, s85, v0
	v_mul_f32_e32 v115, 0x4b800000, v0
	s_nop 0
	v_cndmask_b32_e32 v0, v0, v115, vcc
	v_rsq_f32_e32 v0, v0
	s_nop 0
	v_mul_f32_e32 v115, 0x45800000, v0
	v_cndmask_b32_e32 v161, v0, v115, vcc
	v_mul_f32_e32 v0, v161, v114
	v_cmp_gt_i32_e32 vcc, s22, v157
	v_mul_f32_e32 v0, 0x3db504f3, v0
	s_nop 0
	v_cndmask_b32_e32 v118, v208, v0, vcc
	v_max_f32_e32 v0, v120, v121
	v_max3_f32 v114, v118, v119, v0
	s_nop 1
	v_max_f32_dpp v115, v114, v114 quad_perm:[1,0,3,2] row_mask:0xf bank_mask:0xf
	s_nop 1
	v_max_f32_dpp v116, v115, v115 quad_perm:[2,3,0,1] row_mask:0xf bank_mask:0xf
	s_nop 1
	v_max_f32_dpp v117, v116, v116 row_ror:4 row_mask:0xf bank_mask:0xf
	s_nop 1
	v_max_f32_dpp v172, v117, v117 row_ror:8 row_mask:0xf bank_mask:0xf
	v_xor_b32_e32 v0, 1, v206
	v_xor_b32_e32 v114, 2, v206
	v_xor_b32_e32 v115, 4, v206
	v_xor_b32_e32 v116, 8, v206
	v_max3_f32 v117, v160, v117, v172
	v_sub_f32_e32 v118, v118, v117
	v_sub_f32_e32 v119, v119, v117
	v_sub_f32_e32 v120, v120, v117
	v_sub_f32_e32 v121, v121, v117
	v_mul_f32_e32 v118, 0x3fb8aa3b, v118
	v_mul_f32_e32 v119, 0x3fb8aa3b, v119
	v_mul_f32_e32 v120, 0x3fb8aa3b, v120
	v_mul_f32_e32 v121, 0x3fb8aa3b, v121
	v_exp_f32_e32 v118, v118
	v_exp_f32_e32 v119, v119
	v_exp_f32_e32 v120, v120
	v_exp_f32_e32 v121, v121
	v_sub_f32_e32 v160, v160, v117
	v_mul_f32_e32 v161, v161, v118
	v_mul_f32_e32 v125, v125, v119
	v_mul_f32_e32 v123, v123, v120
	v_mul_f32_e32 v122, v122, v121
	v_mul_f32_e32 v160, 0x3fb8aa3b, v160
	v_cvt_pk_bf16_f32 v161, v161, v1
	ds_write_b16 v155, v161 offset:1024
	v_cvt_pk_bf16_f32 v125, v125, v1
	ds_write_b16 v155, v125 offset:1056
	v_cvt_pk_bf16_f32 v123, v123, v1
	ds_write_b16 v155, v123 offset:1088
	v_cvt_pk_bf16_f32 v122, v122, v1
	ds_write_b16 v155, v122 offset:1120
	v_exp_f32_e32 v122, v160
	s_and_saveexec_b64 s[0:1], s[38:39]
	ds_write_b32 v129, v122 offset:640
	s_or_b64 exec, exec, s[0:1]
	v_add_f32_e32 v118, 0, v118
	v_add_f32_e32 v118, v119, v118
	v_add_f32_e32 v118, v120, v118
	v_add_f32_e32 v118, v121, v118
	v_mov_b32_e32 v119, s56
	v_fmac_f32_e32 v118, v159, v122
	ds_read_b128 v[120:123], v119 offset:640
	v_add_u32_e32 v154, 0x80, v154
	v_add_u32_e32 v157, 64, v157
	s_cmp_eq_u32 s23, s24
	s_waitcnt lgkmcnt(0)
; #define LAS __attribute__((address_space(3)))
;     ...
;           const f32x4 al4 = *(const LAS f32x4*)alf;
; #pragma unroll
;           for (int c = 0; c < 8; ++c) oacc[c] *= al4;
; #pragma unroll
;           for (int ks = 0; ks < 2; ++ks) {
;               const bf16x8 pf = *(const LAS bf16x8*)(pbT + (c16 & 3) * 64 + ks * 32 + quad * 8);
;               u16x4 t0[8], t1[8];
;     ...
;               if (ks == 0) { TRR8(t0, 0, 0); TRR8(t1, 1, 0); } else { TRR8(t0, 0, 8192); TRR8(t1, 1, 8192); }
;     ...
; #pragma unroll
;               for (int c = 0; c < 8; ++c) {
;                   const bf16x8 bf = {(short)t0[c][0], (short)t0[c][1], (short)t0[c][2], (short)t0[c][3], (short)t1[c][0], (short)t1[c][1], (short)t1[c][2], (short)t1[c][3]};
;                   oacc[c] = __builtin_amdgcn_mfma_f32_16x16x32_bf16(pf, bf, oacc[c], 0, 0, 0);
;               }
;           }
	v_pk_mul_f32 v[174:175], v[92:93], v[122:123]
	v_pk_mul_f32 v[172:173], v[90:91], v[120:121]
	v_pk_mul_f32 v[92:93], v[96:97], v[122:123]
	v_pk_mul_f32 v[90:91], v[94:95], v[120:121]
	ds_read_b128 v[94:97], v156 offset:1024
	ds_read_b64_tr_b16 v[216:217], v130 offset:0
	ds_read_b64_tr_b16 v[218:219], v138 offset:0
	ds_read_b64_tr_b16 v[212:213], v131 offset:0
	ds_read_b64_tr_b16 v[214:215], v139 offset:0
	ds_read_b64_tr_b16 v[194:195], v132 offset:0
	ds_read_b64_tr_b16 v[196:197], v140 offset:0
	ds_read_b64_tr_b16 v[190:191], v133 offset:0
	ds_read_b64_tr_b16 v[192:193], v141 offset:0
	ds_read_b64_tr_b16 v[186:187], v134 offset:0
	ds_read_b64_tr_b16 v[188:189], v142 offset:0
	v_pk_mul_f32 v[106:107], v[106:107], v[120:121]
	v_pk_mul_f32 v[110:111], v[110:111], v[120:121]
	v_pk_mul_f32 v[176:177], v[82:83], v[120:121]
	v_pk_mul_f32 v[182:183], v[86:87], v[120:121]
	v_pk_mul_f32 v[86:87], v[102:103], v[120:121]
	v_pk_mul_f32 v[82:83], v[98:99], v[120:121]
	v_pk_mul_f32 v[108:109], v[108:109], v[122:123]
	v_pk_mul_f32 v[112:113], v[112:113], v[122:123]
	v_pk_mul_f32 v[178:179], v[84:85], v[122:123]
	v_pk_mul_f32 v[184:185], v[88:89], v[122:123]
	v_pk_mul_f32 v[88:89], v[104:105], v[122:123]
	v_pk_mul_f32 v[84:85], v[100:101], v[122:123]
	ds_read_b64_tr_b16 v[120:121], v135 offset:0
	ds_read_b64_tr_b16 v[122:123], v143 offset:0
	ds_read_b64_tr_b16 v[102:103], v136 offset:0
	ds_read_b64_tr_b16 v[104:105], v144 offset:0
	s_waitcnt lgkmcnt(12)
	v_mfma_f32_16x16x32_bf16 v[106:109], v[94:97], v[216:219], v[106:109]
	ds_read_b64_tr_b16 v[98:99], v137 offset:0
	ds_read_b64_tr_b16 v[100:101], v145 offset:0
	s_waitcnt lgkmcnt(12)
	v_mfma_f32_16x16x32_bf16 v[110:113], v[94:97], v[212:215], v[110:113]
	s_waitcnt lgkmcnt(10)
	v_mfma_f32_16x16x32_bf16 v[172:175], v[94:97], v[194:197], v[172:175]
	s_waitcnt lgkmcnt(8)
	v_mfma_f32_16x16x32_bf16 v[176:179], v[94:97], v[190:193], v[176:179]
	s_waitcnt lgkmcnt(6)
	v_mfma_f32_16x16x32_bf16 v[182:185], v[94:97], v[186:189], v[182:185]
	s_waitcnt lgkmcnt(4)
	v_mfma_f32_16x16x32_bf16 v[120:123], v[94:97], v[120:123], v[90:93]
	s_waitcnt lgkmcnt(2)
	v_mfma_f32_16x16x32_bf16 v[102:105], v[94:97], v[102:105], v[86:89]
	s_waitcnt lgkmcnt(0)
	v_mfma_f32_16x16x32_bf16 v[98:101], v[94:97], v[98:101], v[82:85]
	ds_read_b128 v[220:223], v156 offset:1088
	ds_read_b64_tr_b16 v[212:213], v130 offset:8192
	ds_read_b64_tr_b16 v[214:215], v138 offset:8192
	ds_read_b64_tr_b16 v[194:195], v131 offset:8192
	ds_read_b64_tr_b16 v[196:197], v139 offset:8192
	ds_read_b64_tr_b16 v[90:91], v132 offset:8192
	ds_read_b64_tr_b16 v[92:93], v140 offset:8192
	ds_read_b64_tr_b16 v[82:83], v133 offset:8192
	ds_read_b64_tr_b16 v[84:85], v141 offset:8192
	ds_read_b64_tr_b16 v[86:87], v134 offset:8192
	ds_read_b64_tr_b16 v[88:89], v142 offset:8192
	ds_read_b64_tr_b16 v[94:95], v135 offset:8192
	ds_read_b64_tr_b16 v[96:97], v143 offset:8192
	ds_read_b64_tr_b16 v[190:191], v136 offset:8192
	ds_read_b64_tr_b16 v[192:193], v144 offset:8192
	s_waitcnt lgkmcnt(12)
	v_mfma_f32_16x16x32_bf16 v[106:109], v[220:223], v[212:215], v[106:109]
	ds_read_b64_tr_b16 v[186:187], v137 offset:8192
	ds_read_b64_tr_b16 v[188:189], v145 offset:8192
	s_waitcnt lgkmcnt(12)
	v_mfma_f32_16x16x32_bf16 v[110:113], v[220:223], v[194:197], v[110:113]
	s_waitcnt lgkmcnt(10)
	v_mfma_f32_16x16x32_bf16 v[90:93], v[220:223], v[90:93], v[172:175]
	s_waitcnt lgkmcnt(8)
	v_mfma_f32_16x16x32_bf16 v[82:85], v[220:223], v[82:85], v[176:179]
	s_waitcnt lgkmcnt(6)
	v_mfma_f32_16x16x32_bf16 v[86:89], v[220:223], v[86:89], v[182:185]
	s_waitcnt lgkmcnt(4)
	v_mfma_f32_16x16x32_bf16 v[94:97], v[220:223], v[94:97], v[120:123]
	s_waitcnt lgkmcnt(2)
	v_mfma_f32_16x16x32_bf16 v[102:105], v[220:223], v[190:193], v[102:105]
	s_waitcnt lgkmcnt(0)
	v_mfma_f32_16x16x32_bf16 v[98:101], v[220:223], v[186:189], v[98:101]
	s_cbranch_scc1 .LBB0_952
	v_mov_b32_e32 v159, v118
	v_mov_b32_e32 v160, v117
	s_branch .LBB0_928
